# adds: q/k chunk tiles of the GLA scan are now loaded by the consumer waves (4 dwordx4 loads issued before their output stores, written to LDS before B2 of the next step); producer waves no longer issu
# speedup vs baseline: 1.0002x; 1.0002x over previous
; __device__ __forceinline__ void gla_scan_phase2(LAS unsigned char* lds, const bf16_t* proj, const float* gbuf, const float* wgu  , const float* bg  ,
;                                                 bf16_t* ob0, bf16_t* ob1) {
;     ...
;             const int cw = wave - 4;
;             bf16_t* ob = dir ? ob1 : ob0;
;             const __amdgpu_buffer_rsrc_t ors = __builtin_amdgcn_make_buffer_rsrc((void*)ob, 0, (unsigned)((size_t)MTOK * DM * 2), 0x00020000);
;             const unsigned ovoff = (unsigned)((r * DM + h * 256 + 64 * cw + 4 * hh) * 2);
;             f32x16 S[2][4];
; #pragma unroll
;             for (int nt2 = 0; nt2 < 2; ++nt2)
; #pragma unroll
;                 for (int kt = 0; kt < 4; ++kt)
; #pragma unroll
;                     for (int i = 0; i < 16; ++i) S[nt2][kt][i] = 0.f;
;             for (int n = 0; n <= NCH; ++n) {
;                 if (n >= 1) {
;                     const int mch = n - 1;
;                     const int tok0 = b * SEQ + (dir ? NCH - 1 - mch : mch) * CH;
.LBB0_213:
	s_ashr_i32 s9, s14, 3
	s_bfe_u32 s15, s14, 0x20001
	s_and_b32 s8, s14, 1
	s_mov_b64 s[6:7], -1
	s_and_b64 vcc, exec, s[12:13]
	s_cbranch_vccz .LBB0_217
	s_cmp_eq_u32 s8, 0
	s_cselect_b64 s[48:49], -1, 0
	v_and_b32_e32 v230, 15, v179
	v_lshlrev_b32_e32 v230, 4, v230
	v_bfe_u32 v231, v179, 4, 2
	v_bfe_u32 v232, v179, 6, 2
	v_lshl_add_u32 v231, v232, 3, v231
	v_mul_u32_u24_e32 v231, 0x1a00, v231
	v_add_u32_e32 v230, v230, v231
	s_lshl_b32 s26, s15, 8
	v_add_u32_e32 v230, s26, v230
	v_lshlrev_b32_e32 v231, 11, v232
	v_add_u32_e32 v231, 0x1b600, v231
	v_and_b32_e32 v232, 63, v179
	v_lshl_add_u32 v231, v232, 4, v231
	s_and_b64 s[82:83], s[48:49], exec
	s_cselect_b32 s26, 1, 62
	s_lshl_b32 s26, s26, 5
	s_lshl_b32 s28, s9, 11
	s_add_i32 s26, s26, s28
	s_mulk_i32 s26, 0x1a00
	s_add_u32 s78, s64, s26
	s_addc_u32 s79, s65, 0
	s_add_u32 s80, s78, 0x6800
	s_addc_u32 s81, s79, 0
	s_add_u32 s82, s78, 0x400
	s_addc_u32 s83, s79, 0
	global_load_dwordx4 v[214:217], v230, s[78:79]
	global_load_dwordx4 v[218:221], v230, s[80:81]
	global_load_dwordx4 v[222:225], v230, s[82:83]
	s_add_u32 s82, s80, 0x400
	s_addc_u32 s83, s81, 0
	global_load_dwordx4 v[226:229], v230, s[82:83]
	s_waitcnt lgkmcnt(0)
	s_barrier
	s_and_b64 s[20:21], s[48:49], exec
	s_waitcnt lgkmcnt(0)
	s_barrier
	v_readlane_b32 s20, v253, 23
	s_waitcnt lgkmcnt(0)
	s_barrier
	v_readlane_b32 s21, v253, 24
	s_waitcnt lgkmcnt(0)
	s_barrier
	s_cselect_b32 s0, s73, s21
	v_lshl_add_u32 v160, s15, 9, v212
	v_mov_b32_e32 v0, 0
	s_mov_b32 s6, 0
	s_cselect_b32 s68, s72, s20
	s_and_b32 s69, s0, 0xffff
	s_lshl_b32 s7, s9, 22
	v_or_b32_e32 v193, 16, v160
	v_or_b32_e32 v234, 32, v160
	v_or_b32_e32 v235, 48, v160
	v_or_b32_e32 v236, 64, v160
	v_or_b32_e32 v237, 0x50, v160
	v_or_b32_e32 v238, 0x60, v160
	v_or_b32_e32 v239, 0x70, v160
	s_mov_b32 s20, 63
	v_mov_b32_e32 v1, v0
	v_mov_b32_e32 v2, v0
	v_mov_b32_e32 v3, v0
	v_mov_b32_e32 v4, v0
	v_mov_b32_e32 v5, v0
	v_mov_b32_e32 v6, v0
	v_mov_b32_e32 v7, v0
	v_mov_b32_e32 v8, v0
	v_mov_b32_e32 v9, v0
	v_mov_b32_e32 v10, v0
	v_mov_b32_e32 v11, v0
	v_mov_b32_e32 v12, v0
	v_mov_b32_e32 v13, v0
	v_mov_b32_e32 v14, v0
	v_mov_b32_e32 v15, v0
	v_mov_b32_e32 v16, v0
	v_mov_b32_e32 v17, v0
	v_mov_b32_e32 v18, v0
	v_mov_b32_e32 v19, v0
	v_mov_b32_e32 v20, v0
	v_mov_b32_e32 v21, v0
	v_mov_b32_e32 v22, v0
	v_mov_b32_e32 v23, v0
	v_mov_b32_e32 v24, v0
	v_mov_b32_e32 v25, v0
	v_mov_b32_e32 v26, v0
	v_mov_b32_e32 v27, v0
	v_mov_b32_e32 v28, v0
	v_mov_b32_e32 v29, v0
	v_mov_b32_e32 v30, v0
	v_mov_b32_e32 v31, v0
	v_mov_b32_e32 v32, v0
	v_mov_b32_e32 v33, v0
	v_mov_b32_e32 v34, v0
	v_mov_b32_e32 v35, v0
	v_mov_b32_e32 v36, v0
	v_mov_b32_e32 v37, v0
	v_mov_b32_e32 v38, v0
	v_mov_b32_e32 v39, v0
	s_waitcnt vmcnt(1)
	v_mov_b32_e32 v40, v0
	v_mov_b32_e32 v41, v0
	v_mov_b32_e32 v42, v0
	v_mov_b32_e32 v43, v0
	s_waitcnt vmcnt(0)
	v_mov_b32_e32 v44, v0
	v_mov_b32_e32 v45, v0
	v_mov_b32_e32 v46, v0
	v_mov_b32_e32 v47, v0
	v_mov_b32_e32 v48, v0
	v_mov_b32_e32 v49, v0
	v_mov_b32_e32 v50, v0
	v_mov_b32_e32 v51, v0
	v_mov_b32_e32 v52, v0
	v_mov_b32_e32 v53, v0
	v_mov_b32_e32 v54, v0
	v_mov_b32_e32 v55, v0
	v_mov_b32_e32 v56, v0
	v_mov_b32_e32 v57, v0
	v_mov_b32_e32 v58, v0
	v_mov_b32_e32 v59, v0
	v_mov_b32_e32 v60, v0
	v_mov_b32_e32 v61, v0
	v_mov_b32_e32 v62, v0
	v_mov_b32_e32 v63, v0
	v_mov_b32_e32 v64, v0
	v_mov_b32_e32 v65, v0
	v_mov_b32_e32 v66, v0
	v_mov_b32_e32 v67, v0
	v_mov_b32_e32 v68, v0
	v_mov_b32_e32 v69, v0
	v_mov_b32_e32 v70, v0
	v_mov_b32_e32 v71, v0
	v_mov_b32_e32 v72, v0
	v_mov_b32_e32 v73, v0
	v_mov_b32_e32 v74, v0
	v_mov_b32_e32 v75, v0
	v_mov_b32_e32 v76, v0
	v_mov_b32_e32 v77, v0
	v_mov_b32_e32 v78, v0
	v_mov_b32_e32 v79, v0
	v_mov_b32_e32 v80, v0
	v_mov_b32_e32 v81, v0
	v_mov_b32_e32 v82, v0
	v_mov_b32_e32 v83, v0
	v_mov_b32_e32 v84, v0
	v_mov_b32_e32 v85, v0
	v_mov_b32_e32 v86, v0
	v_mov_b32_e32 v87, v0
	v_mov_b32_e32 v88, v0
	v_mov_b32_e32 v89, v0
	v_mov_b32_e32 v90, v0
	v_mov_b32_e32 v91, v0
	v_mov_b32_e32 v92, v0
	v_mov_b32_e32 v93, v0
	v_mov_b32_e32 v94, v0
	v_mov_b32_e32 v95, v0
	v_mov_b32_e32 v96, v0
	v_mov_b32_e32 v97, v0
	v_mov_b32_e32 v98, v0
	v_mov_b32_e32 v99, v0
	v_mov_b32_e32 v100, v0
	v_mov_b32_e32 v101, v0
	v_mov_b32_e32 v102, v0
	v_mov_b32_e32 v103, v0
	v_mov_b32_e32 v104, v0
	v_mov_b32_e32 v105, v0
	v_mov_b32_e32 v106, v0
	v_mov_b32_e32 v107, v0
	v_mov_b32_e32 v108, v0
	v_mov_b32_e32 v109, v0
	v_mov_b32_e32 v110, v0
	v_mov_b32_e32 v111, v0
	v_mov_b32_e32 v112, v0
	v_mov_b32_e32 v113, v0
	v_mov_b32_e32 v114, v0
	v_mov_b32_e32 v115, v0
	v_mov_b32_e32 v116, v0
	v_mov_b32_e32 v117, v0
	v_mov_b32_e32 v118, v0
	v_mov_b32_e32 v119, v0
	v_mov_b32_e32 v120, v0
	v_mov_b32_e32 v121, v0
	v_mov_b32_e32 v122, v0
	v_mov_b32_e32 v123, v0
	v_mov_b32_e32 v124, v0
	v_mov_b32_e32 v125, v0
	v_mov_b32_e32 v126, v0
	v_mov_b32_e32 v127, v0
	s_waitcnt vmcnt(0)
; #define LAS __attribute__((address_space(3)))
; #define MFMA32(a, b, c) __builtin_amdgcn_mfma_f32_32x32x16_bf16((a), (b), (c), 0, 0, 0)
; __device__ __forceinline__ void gla_scan_phase2(LAS unsigned char* lds, const bf16_t* proj, const float* gbuf, const float* wgu  , const float* bg  ,
;                                                 bf16_t* ob0, bf16_t* ob1) {
;     ...
;                     bf16x8 bv[2][2];
; #pragma unroll
;                     for (int nt2 = 0; nt2 < 2; ++nt2)
; #pragma unroll
;                         for (int ks = 0; ks < 2; ++ks) bv[nt2][ks] = *(const LAS bf16x8*)(set + G2_VT + (64 * cw + 32 * nt2 + r) * 80 + ks * 32 + hh * 16);
;                     f32x16 oacc[2];
; #pragma unroll
;                     for (int nt2 = 0; nt2 < 2; ++nt2)
; #pragma unroll
;                         for (int i = 0; i < 16; ++i) oacc[nt2][i] = 0.f;
; #pragma unroll
;                     for (int ks = 0; ks < 2; ++ks) {
;                         const bf16x8 a = *(const LAS bf16x8*)(set + G2_SC + r * 80 + ks * 32 + hh * 16);
; #pragma unroll
;                         for (int nt2 = 0; nt2 < 2; ++nt2) oacc[nt2] = MFMA32(bv[nt2][ks], a, oacc[nt2]);
;                     }
.LBB0_215:
	s_and_b64 s[24:25], s[48:49], exec
	s_cselect_b32 s21, s6, s20
	s_bitcmp1_b32 s6, 0
	s_cselect_b32 s0, 0xa800, 0
	s_add_i32 s0, s0, 0
	v_add_u32_e32 v241, s0, v195
	v_add_u32_e32 v166, v241, v210
	ds_read_b128 v[170:173], v166 offset:18944
	ds_read_b128 v[174:177], v166 offset:21504
	v_add_u32_e32 v240, v241, v196
	ds_read_b128 v[128:131], v240 offset:39424
	ds_read_b128 v[162:165], v166 offset:18976
	ds_read_b128 v[242:245], v240 offset:39456
	ds_read_b128 v[166:169], v166 offset:21536
	v_add3_u32 v250, s0, v197, v188
	s_waitcnt lgkmcnt(3)
	v_mfma_f32_32x32x16_bf16 v[144:159], v[170:173], v[128:131], 0
	v_mfma_f32_32x32x16_bf16 v[128:143], v[174:177], v[128:131], 0
	s_waitcnt lgkmcnt(1)
	v_mfma_f32_32x32x16_bf16 v[144:159], v[162:165], v[242:245], v[144:159]
	s_waitcnt lgkmcnt(0)
	v_mfma_f32_32x32x16_bf16 v[128:143], v[166:169], v[242:245], v[128:143]
	ds_read2_b64 v[242:245], v250 offset1:2
	v_cvt_pk_bf16_f32 v246, v112, v113
	v_cvt_pk_bf16_f32 v247, v114, v115
	v_cvt_pk_bf16_f32 v248, v116, v117
	v_cvt_pk_bf16_f32 v249, v118, v119
	s_waitcnt lgkmcnt(0)
	s_nop 0
	v_mfma_f32_32x32x16_bf16 v[144:159], v[246:249], v[242:245], v[144:159]
	v_cvt_pk_bf16_f32 v246, v48, v49
	v_cvt_pk_bf16_f32 v247, v50, v51
	v_cvt_pk_bf16_f32 v248, v52, v53
	v_cvt_pk_bf16_f32 v249, v54, v55
	s_nop 1
	v_mfma_f32_32x32x16_bf16 v[128:143], v[246:249], v[242:245], v[128:143]
	ds_read2_b64 v[242:245], v250 offset0:4 offset1:6
	v_cvt_pk_bf16_f32 v246, v120, v121
	v_cvt_pk_bf16_f32 v247, v122, v123
	v_cvt_pk_bf16_f32 v248, v124, v125
	v_cvt_pk_bf16_f32 v249, v126, v127
	s_waitcnt lgkmcnt(0)
	s_barrier
	s_waitcnt lgkmcnt(0)
	v_mfma_f32_32x32x16_bf16 v[144:159], v[246:249], v[242:245], v[144:159]
	v_cvt_pk_bf16_f32 v246, v56, v57
	v_cvt_pk_bf16_f32 v247, v58, v59
	v_cvt_pk_bf16_f32 v248, v60, v61
	v_cvt_pk_bf16_f32 v249, v62, v63
	s_nop 1
	v_mfma_f32_32x32x16_bf16 v[128:143], v[246:249], v[242:245], v[128:143]
	ds_read2_b64 v[242:245], v250 offset0:8 offset1:10
	v_cvt_pk_bf16_f32 v246, v96, v97
	v_cvt_pk_bf16_f32 v247, v98, v99
	v_cvt_pk_bf16_f32 v248, v100, v101
	v_cvt_pk_bf16_f32 v249, v102, v103
	s_waitcnt lgkmcnt(0)
	s_nop 0
	v_mfma_f32_32x32x16_bf16 v[144:159], v[246:249], v[242:245], v[144:159]
	v_cvt_pk_bf16_f32 v246, v32, v33
	v_cvt_pk_bf16_f32 v247, v34, v35
	v_cvt_pk_bf16_f32 v248, v36, v37
	v_cvt_pk_bf16_f32 v249, v38, v39
	s_nop 1
	v_mfma_f32_32x32x16_bf16 v[128:143], v[246:249], v[242:245], v[128:143]
	ds_read2_b64 v[242:245], v250 offset0:12 offset1:14
	v_cvt_pk_bf16_f32 v246, v104, v105
	v_cvt_pk_bf16_f32 v247, v106, v107
	v_cvt_pk_bf16_f32 v248, v108, v109
	v_cvt_pk_bf16_f32 v249, v110, v111
	s_waitcnt lgkmcnt(0)
	s_nop 0
	v_mfma_f32_32x32x16_bf16 v[144:159], v[246:249], v[242:245], v[144:159]
	v_cvt_pk_bf16_f32 v246, v40, v41
	v_cvt_pk_bf16_f32 v247, v42, v43
	v_cvt_pk_bf16_f32 v248, v44, v45
	v_cvt_pk_bf16_f32 v249, v46, v47
	s_nop 1
	v_mfma_f32_32x32x16_bf16 v[128:143], v[246:249], v[242:245], v[128:143]
	ds_read2_b64 v[242:245], v250 offset0:16 offset1:18
	v_cvt_pk_bf16_f32 v246, v80, v81
	v_cvt_pk_bf16_f32 v247, v82, v83
	v_cvt_pk_bf16_f32 v248, v84, v85
	v_cvt_pk_bf16_f32 v249, v86, v87
	s_waitcnt lgkmcnt(0)
	s_nop 0
	v_mfma_f32_32x32x16_bf16 v[144:159], v[246:249], v[242:245], v[144:159]
	v_cvt_pk_bf16_f32 v246, v16, v17
	v_cvt_pk_bf16_f32 v247, v18, v19
	v_cvt_pk_bf16_f32 v248, v20, v21
	v_cvt_pk_bf16_f32 v249, v22, v23
	s_nop 1
	v_mfma_f32_32x32x16_bf16 v[128:143], v[246:249], v[242:245], v[128:143]
	ds_read2_b64 v[242:245], v250 offset0:20 offset1:22
	v_cvt_pk_bf16_f32 v246, v88, v89
	v_cvt_pk_bf16_f32 v247, v90, v91
	v_cvt_pk_bf16_f32 v248, v92, v93
	v_cvt_pk_bf16_f32 v249, v94, v95
	s_waitcnt vmcnt(8)
	ds_write_b128 v231, v[214:217]
	ds_write_b128 v231, v[218:221] offset:1024
	ds_write_b128 v231, v[222:225] offset:8192
	ds_write_b128 v231, v[226:229] offset:9216
	s_waitcnt lgkmcnt(0)
	s_barrier
	s_cmp_gt_u32 s6, 61
	s_cbranch_scc1 .Lc_ld_skip
	s_and_b64 s[82:83], s[48:49], exec
	s_cselect_b32 s26, s6, s20
	s_cselect_b32 s28, 2, -2
	s_add_i32 s26, s26, s28
	s_lshl_b32 s26, s26, 5
	s_lshl_b32 s28, s9, 11
	s_add_i32 s26, s26, s28
	s_mulk_i32 s26, 0x1a00
	s_add_u32 s78, s64, s26
	s_addc_u32 s79, s65, 0
	s_add_u32 s80, s78, 0x6800
	s_addc_u32 s81, s79, 0
	s_add_u32 s82, s78, 0x400
	s_addc_u32 s83, s79, 0
	global_load_dwordx4 v[214:217], v230, s[78:79]
	global_load_dwordx4 v[218:221], v230, s[80:81]
	global_load_dwordx4 v[222:225], v230, s[82:83]
	s_add_u32 s82, s80, 0x400
	s_addc_u32 s83, s81, 0
	global_load_dwordx4 v[226:229], v230, s[82:83]
; __device__ __forceinline__ unsigned pk2(float lo, float hi) { f32x2 v = {lo, hi}; bf16x2_t b = __builtin_convertvector(v, bf16x2_t); return __builtin_bit_cast(unsigned, b); }
; #define G2_BAR() do { asm volatile("s_waitcnt lgkmcnt(0)" ::: "memory"); __builtin_amdgcn_s_barrier(); asm volatile("" ::: "memory"); } while (0)
; __device__ __forceinline__ void gla_scan_phase2(LAS unsigned char* lds, const bf16_t* proj, const float* gbuf, const float* wgu  , const float* bg  ,
;                                                 bf16_t* ob0, bf16_t* ob1) {
;     ...
;                     G2_OINTER(0);
;                     G2_BAR();
;                     G2_OINTER(1); G2_OINTER(2);
;                     G2_BAR();
;                     G2_OINTER(3);
;                     {
;                         const unsigned orow = (unsigned)tok0 * (unsigned)(DM * 2);
; #pragma unroll
;                         for (int nt2 = 0; nt2 < 2; ++nt2)
; #pragma unroll
;                             for (int g = 0; g < 4; ++g) {
;                                 u32x2 w; w.x = pk2(oacc[nt2][4 * g], oacc[nt2][4 * g + 1]); w.y = pk2(oacc[nt2][4 * g + 2], oacc[nt2][4 * g + 3]);
;                                 __builtin_amdgcn_raw_buffer_store_b64(w, ors, ovoff + (unsigned)((32 * nt2 + 8 * g) * 2), orow, 0);
;                             }
;                     }
.Lc_ld_skip:
	s_waitcnt lgkmcnt(0)
	v_mfma_f32_32x32x16_bf16 v[144:159], v[246:249], v[242:245], v[144:159]
	v_cvt_pk_bf16_f32 v246, v24, v25
	v_cvt_pk_bf16_f32 v247, v26, v27
	v_cvt_pk_bf16_f32 v248, v28, v29
	v_cvt_pk_bf16_f32 v249, v30, v31
	s_nop 1
	v_mfma_f32_32x32x16_bf16 v[128:143], v[246:249], v[242:245], v[128:143]
	ds_read2_b64 v[242:245], v250 offset0:24 offset1:26
	v_cvt_pk_bf16_f32 v246, v64, v65
	v_cvt_pk_bf16_f32 v247, v66, v67
	v_cvt_pk_bf16_f32 v248, v68, v69
	v_cvt_pk_bf16_f32 v249, v70, v71
	s_waitcnt lgkmcnt(0)
	s_nop 0
	v_mfma_f32_32x32x16_bf16 v[144:159], v[246:249], v[242:245], v[144:159]
	v_cvt_pk_bf16_f32 v246, v0, v1
	v_cvt_pk_bf16_f32 v247, v2, v3
	v_cvt_pk_bf16_f32 v248, v4, v5
	v_cvt_pk_bf16_f32 v249, v6, v7
	s_nop 1
	v_mfma_f32_32x32x16_bf16 v[128:143], v[246:249], v[242:245], v[128:143]
	ds_read2_b64 v[242:245], v250 offset0:28 offset1:30
	v_cvt_pk_bf16_f32 v246, v72, v73
	v_cvt_pk_bf16_f32 v247, v74, v75
	v_cvt_pk_bf16_f32 v248, v76, v77
	v_cvt_pk_bf16_f32 v249, v78, v79
	s_lshl_b32 s0, s21, 16
	s_add_i32 s0, s0, s7
	s_waitcnt lgkmcnt(0)
	v_mfma_f32_32x32x16_bf16 v[144:159], v[246:249], v[242:245], v[144:159]
	v_cvt_pk_bf16_f32 v246, v8, v9
	v_cvt_pk_bf16_f32 v247, v10, v11
	v_cvt_pk_bf16_f32 v248, v12, v13
	v_cvt_pk_bf16_f32 v249, v14, v15
	s_add_i32 s6, s6, 1
	s_add_i32 s20, s20, -1
	s_cmp_eq_u32 s6, 64
	v_mfma_f32_32x32x16_bf16 v[128:143], v[246:249], v[242:245], v[128:143]
	s_nop 3
	v_cvt_pk_bf16_f32 v144, v144, v145
	v_cvt_pk_bf16_f32 v145, v146, v147
	buffer_store_dwordx2 v[144:145], v160, s[68:71], s0 offen
	v_cvt_pk_bf16_f32 v144, v148, v149
	v_cvt_pk_bf16_f32 v145, v150, v151
	buffer_store_dwordx2 v[144:145], v193, s[68:71], s0 offen
	v_cvt_pk_bf16_f32 v144, v152, v153
	v_cvt_pk_bf16_f32 v145, v154, v155
	buffer_store_dwordx2 v[144:145], v234, s[68:71], s0 offen
	v_cvt_pk_bf16_f32 v144, v156, v157
	v_cvt_pk_bf16_f32 v145, v158, v159
	v_cvt_pk_bf16_f32 v128, v128, v129
	v_cvt_pk_bf16_f32 v129, v130, v131
	buffer_store_dwordx2 v[144:145], v235, s[68:71], s0 offen
	buffer_store_dwordx2 v[128:129], v236, s[68:71], s0 offen
	v_cvt_pk_bf16_f32 v128, v132, v133
	v_cvt_pk_bf16_f32 v129, v134, v135
	buffer_store_dwordx2 v[128:129], v237, s[68:71], s0 offen
	v_cvt_pk_bf16_f32 v128, v136, v137
	v_cvt_pk_bf16_f32 v129, v138, v139
	buffer_store_dwordx2 v[128:129], v238, s[68:71], s0 offen
	v_cvt_pk_bf16_f32 v128, v140, v141
	v_cvt_pk_bf16_f32 v129, v142, v143
	buffer_store_dwordx2 v[128:129], v239, s[68:71], s0 offen
	ds_read_b128 v[128:131], v241 offset:41984
	ds_read_b128 v[132:135], v241 offset:42016
	ds_read_b128 v[136:139], v241 offset:42048
	ds_read_b128 v[140:143], v241 offset:42080
	s_waitcnt lgkmcnt(3)
	v_pk_mul_f32 v[114:115], v[114:115], v[130:131]
	s_waitcnt lgkmcnt(2)
	v_pk_mul_f32 v[118:119], v[118:119], v[134:135]
	v_pk_mul_f32 v[116:117], v[116:117], v[132:133]
	v_pk_mul_f32 v[112:113], v[112:113], v[128:129]
	v_pk_mul_f32 v[54:55], v[54:55], v[134:135]
	v_pk_mul_f32 v[50:51], v[50:51], v[130:131]
	v_pk_mul_f32 v[52:53], v[52:53], v[132:133]
	v_pk_mul_f32 v[48:49], v[48:49], v[128:129]
	ds_read_b128 v[128:131], v240 offset:8704
	ds_read_b128 v[132:135], v240 offset:8736
	s_waitcnt lgkmcnt(2)
	v_pk_mul_f32 v[126:127], v[126:127], v[142:143]
	v_pk_mul_f32 v[122:123], v[122:123], v[138:139]
	v_pk_mul_f32 v[124:125], v[124:125], v[140:141]
	v_pk_mul_f32 v[120:121], v[120:121], v[136:137]
	v_pk_mul_f32 v[62:63], v[62:63], v[142:143]
	v_pk_mul_f32 v[58:59], v[58:59], v[138:139]
	v_pk_mul_f32 v[60:61], v[60:61], v[140:141]
	v_pk_mul_f32 v[56:57], v[56:57], v[136:137]
	s_waitcnt lgkmcnt(1)
	v_mfma_f32_32x32x16_bf16 v[112:127], v[128:131], v[170:173], v[112:127]
	v_mfma_f32_32x32x16_bf16 v[48:63], v[128:131], v[174:177], v[48:63]
	s_waitcnt lgkmcnt(0)
	v_mfma_f32_32x32x16_bf16 v[112:127], v[132:135], v[162:165], v[112:127]
	v_mfma_f32_32x32x16_bf16 v[48:63], v[132:135], v[166:169], v[48:63]
	ds_read_b128 v[128:131], v241 offset:42112
	ds_read_b128 v[132:135], v241 offset:42144
	ds_read_b128 v[136:139], v241 offset:42176
	ds_read_b128 v[140:143], v241 offset:42208
	s_waitcnt lgkmcnt(3)
	v_pk_mul_f32 v[98:99], v[98:99], v[130:131]
	v_pk_mul_f32 v[96:97], v[96:97], v[128:129]
	v_pk_mul_f32 v[34:35], v[34:35], v[130:131]
	v_pk_mul_f32 v[32:33], v[32:33], v[128:129]
	ds_read_b128 v[128:131], v240 offset:11264
	s_waitcnt lgkmcnt(1)
	v_pk_mul_f32 v[110:111], v[110:111], v[142:143]
	v_pk_mul_f32 v[106:107], v[106:107], v[138:139]
	v_pk_mul_f32 v[102:103], v[102:103], v[134:135]
	v_pk_mul_f32 v[108:109], v[108:109], v[140:141]
	v_pk_mul_f32 v[104:105], v[104:105], v[136:137]
	v_pk_mul_f32 v[100:101], v[100:101], v[132:133]
	v_pk_mul_f32 v[46:47], v[46:47], v[142:143]
	v_pk_mul_f32 v[42:43], v[42:43], v[138:139]
	v_pk_mul_f32 v[38:39], v[38:39], v[134:135]
	v_pk_mul_f32 v[44:45], v[44:45], v[140:141]
	v_pk_mul_f32 v[40:41], v[40:41], v[136:137]
	v_pk_mul_f32 v[36:37], v[36:37], v[132:133]
	s_waitcnt lgkmcnt(0)
	v_mfma_f32_32x32x16_bf16 v[96:111], v[128:131], v[170:173], v[96:111]
	v_mfma_f32_32x32x16_bf16 v[32:47], v[128:131], v[174:177], v[32:47]
	ds_read_b128 v[128:131], v240 offset:11296
	s_waitcnt lgkmcnt(0)
	s_barrier
; #define G2_BAR() do { asm volatile("s_waitcnt lgkmcnt(0)" ::: "memory"); __builtin_amdgcn_s_barrier(); asm volatile("" ::: "memory"); } while (0)
; __device__ __forceinline__ void gla_scan_phase2(LAS unsigned char* lds, const bf16_t* proj, const float* gbuf, const float* wgu  , const float* bg  ,
;                                                 bf16_t* ob0, bf16_t* ob1) {
;     ...
;                     G2_STATE(0); G2_STATE(1);
;                     G2_BAR();
;                     G2_STATE(2); G2_STATE(3);
;     ...
;                     G2_BAR();
	s_waitcnt lgkmcnt(0)
	v_mfma_f32_32x32x16_bf16 v[96:111], v[128:131], v[162:165], v[96:111]
	v_mfma_f32_32x32x16_bf16 v[32:47], v[128:131], v[166:169], v[32:47]
	ds_read_b128 v[128:131], v241 offset:42240
	ds_read_b128 v[132:135], v241 offset:42272
	ds_read_b128 v[136:139], v241 offset:42304
	ds_read_b128 v[140:143], v241 offset:42336
	s_waitcnt lgkmcnt(3)
	v_pk_mul_f32 v[82:83], v[82:83], v[130:131]
	s_waitcnt lgkmcnt(2)
	v_pk_mul_f32 v[86:87], v[86:87], v[134:135]
	v_pk_mul_f32 v[84:85], v[84:85], v[132:133]
	v_pk_mul_f32 v[80:81], v[80:81], v[128:129]
	v_pk_mul_f32 v[22:23], v[22:23], v[134:135]
	v_pk_mul_f32 v[18:19], v[18:19], v[130:131]
	v_pk_mul_f32 v[20:21], v[20:21], v[132:133]
	v_pk_mul_f32 v[16:17], v[16:17], v[128:129]
	ds_read_b128 v[128:131], v240 offset:13824
	ds_read_b128 v[132:135], v240 offset:13856
	s_waitcnt lgkmcnt(2)
	v_pk_mul_f32 v[94:95], v[94:95], v[142:143]
	v_pk_mul_f32 v[90:91], v[90:91], v[138:139]
	v_pk_mul_f32 v[92:93], v[92:93], v[140:141]
	v_pk_mul_f32 v[88:89], v[88:89], v[136:137]
	v_pk_mul_f32 v[30:31], v[30:31], v[142:143]
	v_pk_mul_f32 v[26:27], v[26:27], v[138:139]
	v_pk_mul_f32 v[28:29], v[28:29], v[140:141]
	v_pk_mul_f32 v[24:25], v[24:25], v[136:137]
	s_waitcnt lgkmcnt(1)
	v_mfma_f32_32x32x16_bf16 v[80:95], v[128:131], v[170:173], v[80:95]
	v_mfma_f32_32x32x16_bf16 v[16:31], v[128:131], v[174:177], v[16:31]
	s_waitcnt lgkmcnt(0)
	v_mfma_f32_32x32x16_bf16 v[80:95], v[132:135], v[162:165], v[80:95]
	v_mfma_f32_32x32x16_bf16 v[16:31], v[132:135], v[166:169], v[16:31]
	ds_read_b128 v[128:131], v241 offset:42368
	ds_read_b128 v[132:135], v241 offset:42400
	ds_read_b128 v[136:139], v241 offset:42432
	ds_read_b128 v[140:143], v241 offset:42464
	s_waitcnt lgkmcnt(3)
	v_pk_mul_f32 v[66:67], v[66:67], v[130:131]
	v_pk_mul_f32 v[64:65], v[64:65], v[128:129]
	v_pk_mul_f32 v[2:3], v[2:3], v[130:131]
	v_pk_mul_f32 v[0:1], v[0:1], v[128:129]
	ds_read_b128 v[128:131], v240 offset:16384
	s_waitcnt lgkmcnt(1)
	v_pk_mul_f32 v[78:79], v[78:79], v[142:143]
	v_pk_mul_f32 v[74:75], v[74:75], v[138:139]
	v_pk_mul_f32 v[70:71], v[70:71], v[134:135]
	v_pk_mul_f32 v[76:77], v[76:77], v[140:141]
	v_pk_mul_f32 v[72:73], v[72:73], v[136:137]
	v_pk_mul_f32 v[68:69], v[68:69], v[132:133]
	v_pk_mul_f32 v[14:15], v[14:15], v[142:143]
	v_pk_mul_f32 v[10:11], v[10:11], v[138:139]
	v_pk_mul_f32 v[6:7], v[6:7], v[134:135]
	v_pk_mul_f32 v[12:13], v[12:13], v[140:141]
	v_pk_mul_f32 v[8:9], v[8:9], v[136:137]
	v_pk_mul_f32 v[4:5], v[4:5], v[132:133]
	s_waitcnt lgkmcnt(0)
	v_mfma_f32_32x32x16_bf16 v[64:79], v[128:131], v[170:173], v[64:79]
	v_mfma_f32_32x32x16_bf16 v[0:15], v[128:131], v[174:177], v[0:15]
	ds_read_b128 v[128:131], v240 offset:16416
	s_waitcnt lgkmcnt(0)
	s_barrier
	s_waitcnt lgkmcnt(0)
	v_mfma_f32_32x32x16_bf16 v[64:79], v[128:131], v[162:165], v[64:79]
	v_mfma_f32_32x32x16_bf16 v[0:15], v[128:131], v[166:169], v[0:15]
	s_cbranch_scc0 .LBB0_215
	s_mov_b64 s[6:7], 0
